# RMS+forget loop: DPP sum-of-squares reduction (no ds_bpermute chain), forget-bias load hoisted, counted loop-top wait
# baseline (speedup 1.0000x reference)
.LBB0_638:
	s_or_b64 exec, exec, s[24:25]
	v_ashrrev_i32_e32 v0, 6, v2
	v_readlane_b32 s4, v254, 18
	s_waitcnt vmcnt(0) lgkmcnt(0)
	s_barrier
	v_add_u32_e32 v142, s4, v0
	s_mov_b32 s4, 0x8100
	v_cmp_gt_i32_e32 vcc, s4, v142
	s_and_saveexec_b64 s[24:25], vcc
	s_cbranch_execz .LBB0_649
	v_and_b32_e32 v0, 64, v218
	v_add_u32_e32 v0, 64, v0
	v_xor_b32_e32 v3, 1, v218
	v_cmp_lt_i32_e32 vcc, v3, v0
	s_add_u32 s48, s44, 0x8000000
	s_addc_u32 s49, s45, 0
	v_cndmask_b32_e32 v3, v218, v3, vcc
	v_lshlrev_b32_e32 v160, 2, v3
	v_xor_b32_e32 v3, 2, v218
	v_cmp_lt_i32_e32 vcc, v3, v0
	s_lshl_b32 s28, s64, 3
	s_lshl_b64 s[4:5], s[28:29], 2
	v_cndmask_b32_e32 v3, v218, v3, vcc
	v_lshlrev_b32_e32 v161, 2, v3
	v_xor_b32_e32 v3, 4, v218
	v_cmp_lt_i32_e32 vcc, v3, v0
	s_add_u32 s8, s38, s4
	v_and_b32_e32 v130, 63, v2
	v_cndmask_b32_e32 v3, v218, v3, vcc
	v_lshlrev_b32_e32 v162, 2, v3
	v_xor_b32_e32 v3, 8, v218
	v_cmp_lt_i32_e32 vcc, v3, v0
	s_addc_u32 s9, s39, s5
	v_lshl_add_u32 v126, v130, 4, 0
	v_cndmask_b32_e32 v3, v218, v3, vcc
	v_lshlrev_b32_e32 v163, 2, v3
	v_xor_b32_e32 v3, 16, v218
	v_cmp_lt_i32_e32 vcc, v3, v0
	s_lshl_b64 s[4:5], s[64:65], 20
	s_add_u32 s4, s44, s4
	v_cndmask_b32_e32 v3, v218, v3, vcc
	v_lshlrev_b32_e32 v164, 2, v3
	v_xor_b32_e32 v3, 32, v218
	v_cmp_lt_i32_e32 vcc, v3, v0
	s_addc_u32 s5, s45, s5
	s_add_u32 s4, s4, 0x1831c000
	v_cndmask_b32_e32 v0, v218, v3, vcc
	v_lshlrev_b32_e32 v165, 2, v0
	v_and_b32_e32 v0, 1, v2
	v_and_b32_e32 v3, 2, v2
	v_cmp_eq_u32_e32 vcc, 0, v0
	v_lshlrev_b32_e32 v0, 2, v130
	v_cmp_eq_u32_e64 s[38:39], 0, v3
	v_and_b32_e32 v3, 4, v2
	v_xor_b32_e32 v166, 4, v0
	v_xor_b32_e32 v167, 8, v0
	v_cmp_eq_u32_e64 s[40:41], 0, v3
	v_xor_b32_e32 v168, 16, v0
	v_xor_b32_e32 v169, 32, v0
	v_xor_b32_e32 v170, 64, v0
	v_xor_b32_e32 v171, 0x80, v0
	v_bfrev_b32_e32 v0, v2
	ds_read_b128 v[2:5], v126
	ds_read_b128 v[6:9], v126 offset:1024
	ds_read_b128 v[10:13], v126 offset:2048
	ds_read_b128 v[14:17], v126 offset:3072
	ds_read_b128 v[18:21], v126 offset:4096
	ds_read_b128 v[22:25], v126 offset:5120
	ds_read_b128 v[26:29], v126 offset:6144
	ds_read_b128 v[30:33], v126 offset:7168
	ds_read_b128 v[34:37], v126 offset:8192
	ds_read_b128 v[38:41], v126 offset:9216
	ds_read_b128 v[42:45], v126 offset:10240
	ds_read_b128 v[46:49], v126 offset:11264
	ds_read_b128 v[50:53], v126 offset:12288
	ds_read_b128 v[54:57], v126 offset:13312
	ds_read_b128 v[58:61], v126 offset:14336
	ds_read_b128 v[62:65], v126 offset:15360
	ds_read_b128 v[66:69], v126 offset:16384
	ds_read_b128 v[70:73], v126 offset:17408
	ds_read_b128 v[74:77], v126 offset:18432
	ds_read_b128 v[78:81], v126 offset:19456
	ds_read_b128 v[82:85], v126 offset:20480
	ds_read_b128 v[86:89], v126 offset:21504
	ds_read_b128 v[90:93], v126 offset:22528
	ds_read_b128 v[94:97], v126 offset:23552
	ds_read_b128 v[98:101], v126 offset:24576
	ds_read_b128 v[102:105], v126 offset:25600
	ds_read_b128 v[106:109], v126 offset:26624
	ds_read_b128 v[110:113], v126 offset:27648
	ds_read_b128 v[114:117], v126 offset:28672
	ds_read_b128 v[118:121], v126 offset:29696
	ds_read_b128 v[122:125], v126 offset:30720
	ds_read_b128 v[126:129], v126 offset:31744
	s_addc_u32 s5, s5, 0
	s_lshl_b64 s[10:11], s[64:65], 13
	s_add_u32 s10, s44, s10
	v_lshrrev_b32_e32 v132, 29, v0
	s_addc_u32 s11, s45, s11
	v_lshlrev_b32_e32 v0, 2, v132
	v_ashrrev_i32_e32 v143, 31, v142
	s_add_u32 s28, s10, 0x1871c000
	v_lshl_add_u64 v[144:145], s[8:9], 0, v[0:1]
	global_load_dword v241, v[144:145], off
	v_lshlrev_b32_e32 v0, 3, v130
	v_lshlrev_b64 v[134:135], 12, v[142:143]
	s_addc_u32 s52, s11, 0
	v_cmp_gt_u32_e64 s[42:43], 8, v130
	v_lshl_add_u64 v[146:147], s[78:79], 0, v[0:1]
	v_lshl_add_u64 v[148:149], s[44:45], 0, v[134:135]
	s_mov_b64 s[50:51], 0
	v_lshlrev_b32_e32 v0, 4, v130
	v_lshlrev_b32_e32 v150, 2, v132
	s_mov_b64 s[100:101], s[44:45]
	v_lshl_or_b32 v240, v142, 12, v0
	global_load_dwordx4 v[224:227], v240, s[100:101]
	global_load_dwordx4 v[228:231], v240, s[100:101] offset:1024
	global_load_dwordx4 v[232:235], v240, s[100:101] offset:2048
	global_load_dwordx4 v[236:239], v240, s[100:101] offset:3072
	s_waitcnt vmcnt(0)
	s_branch .LBB0_642

.LBB0_642:
	s_waitcnt vmcnt(5)
	s_mov_b32 s8, 0x8000
	v_cmp_gt_i32_e64 s[44:45], s8, v142
	v_cmp_lt_i32_e64 s[46:47], s91, v142
	v_add_u32_e32 v152, 0xffff8000, v142
	v_mov_b64_e32 v[154:155], v[142:143]
	s_waitcnt lgkmcnt(0)
	v_mov_b64_e32 v[130:131], v[148:149]
	s_and_saveexec_b64 s[54:55], s[46:47]
	v_mov_b32_e32 v153, v1
	v_lshlrev_b64 v[130:131], 12, v[152:153]
	v_lshl_add_u64 v[130:131], s[48:49], 0, v[130:131]
	v_mov_b32_e32 v154, v142
	v_mov_b32_e32 v155, v1
	s_or_b64 exec, exec, s[54:55]
	v_lshl_add_u64 v[130:131], v[130:131], 0, v[0:1]
	v_mov_b64_e32 v[172:173], v[224:225]
	v_mov_b64_e32 v[174:175], v[226:227]
	v_mov_b64_e32 v[138:139], v[228:229]
	v_mov_b64_e32 v[140:141], v[230:231]
	s_mov_b32 s8, 0x800000
	v_pk_mul_f32 v[132:133], v[174:175], v[174:175]
	v_pk_mul_f32 v[134:135], v[172:173], v[172:173]
	s_nop 0
	v_pk_mov_b32 v[136:137], v[134:135], v[132:133] op_sel:[1,0]
	v_mov_b32_e32 v135, v133
	v_pk_add_f32 v[156:157], v[136:137], v[134:135]
	v_pk_mul_f32 v[132:133], v[140:141], v[140:141]
	v_pk_mul_f32 v[134:135], v[138:139], v[138:139]
	v_pk_add_f32 v[156:157], v[156:157], v[156:157] op_sel:[0,1] op_sel_hi:[1,0]
	v_pk_mov_b32 v[136:137], v[134:135], v[132:133] op_sel:[1,0]
	v_mov_b32_e32 v135, v133
	v_pk_add_f32 v[158:159], v[136:137], v[134:135]
	v_mov_b64_e32 v[134:135], v[232:233]
	v_mov_b64_e32 v[136:137], v[234:235]
	s_nop 0
	v_mov_b64_e32 v[130:131], v[236:237]
	v_mov_b64_e32 v[132:133], v[238:239]
	v_readlane_b32 s10, v254, 55
	s_mov_b32 s11, 0x80ff
	v_add_u32_e32 v240, s10, v142
	v_min_i32_e32 v240, s11, v240
	v_lshl_or_b32 v240, v240, 12, v0
	global_load_dwordx4 v[224:227], v240, s[100:101]
	global_load_dwordx4 v[228:231], v240, s[100:101] offset:1024
	global_load_dwordx4 v[232:235], v240, s[100:101] offset:2048
	global_load_dwordx4 v[236:239], v240, s[100:101] offset:3072
	v_pk_add_f32 v[158:159], v[158:159], v[158:159] op_sel:[0,1] op_sel_hi:[1,0]
	v_mul_f32_e32 v151, v130, v130
	v_mul_f32_e32 v153, v131, v131
	v_mov_b32_e32 v157, v151
	v_mov_b32_e32 v159, v153
	v_pk_add_f32 v[156:157], v[156:157], v[158:159]
	v_mul_f32_e32 v158, v135, v135
	v_mul_f32_e32 v176, v132, v132
	v_pk_fma_f32 v[158:159], v[134:135], v[134:135], v[158:159] op_sel_hi:[1,1,0]
	v_mul_f32_e32 v178, v133, v133
	v_mov_b32_e32 v159, v176
	v_mul_f32_e32 v176, v137, v137
	v_pk_fma_f32 v[176:177], v[136:137], v[136:137], v[176:177] op_sel_hi:[1,1,0]
	s_nop 0
	v_mov_b32_e32 v177, v178
	v_pk_add_f32 v[158:159], v[158:159], v[176:177]
	v_lshlrev_b64 v[178:179], 11, v[154:155]
	v_pk_add_f32 v[156:157], v[156:157], v[158:159]
	s_nop 0
	v_add_f32_e32 v151, v156, v157
	s_nop 1
	v_add_f32_dpp v151, v151, v151 quad_perm:[1,0,3,2] row_mask:0xf bank_mask:0xf
	s_nop 1
	v_add_f32_dpp v151, v151, v151 quad_perm:[2,3,0,1] row_mask:0xf bank_mask:0xf
	s_nop 1
	v_add_f32_dpp v151, v151, v151 row_half_mirror row_mask:0xf bank_mask:0xf
	s_nop 1
	v_add_f32_dpp v151, v151, v151 row_mirror row_mask:0xf bank_mask:0xf
	s_nop 1
	v_add_f32_dpp v151, v151, v151 row_bcast:15 row_mask:0xa bank_mask:0xf
	s_nop 1
	v_add_f32_dpp v151, v151, v151 row_bcast:31 row_mask:0xc bank_mask:0xf
	s_nop 1
	v_readlane_b32 s10, v151, 63
	s_nop 0
	v_mov_b32_e32 v151, s10
	v_fmamk_f32 v151, v151, 0x3a800000, v206
	v_cmp_gt_f32_e64 s[46:47], s8, v151
	v_mul_f32_e32 v153, 0x4b800000, v151
	s_nop 0
	v_cndmask_b32_e64 v151, v151, v153, s[46:47]
	v_rsq_f32_e32 v151, v151
	s_nop 0
	v_mul_f32_e32 v153, 0x45800000, v151
	v_cndmask_b32_e64 v176, v151, v153, s[46:47]
	v_pk_mul_f32 v[156:157], v[174:175], v[176:177] op_sel_hi:[1,0]
	v_pk_mul_f32 v[158:159], v[172:173], v[176:177] op_sel_hi:[1,0]
	v_and_b32_sdwa v172, v157, v205 dst_sel:DWORD dst_unused:UNUSED_PAD src0_sel:WORD_1 src1_sel:DWORD
	v_and_b32_sdwa v173, v159, v205 dst_sel:DWORD dst_unused:UNUSED_PAD src0_sel:WORD_1 src1_sel:DWORD
	v_and_b32_sdwa v151, v156, v205 dst_sel:DWORD dst_unused:UNUSED_PAD src0_sel:WORD_1 src1_sel:DWORD
	v_and_b32_sdwa v153, v158, v205 dst_sel:DWORD dst_unused:UNUSED_PAD src0_sel:WORD_1 src1_sel:DWORD
	v_add3_u32 v172, v157, v172, s91
	v_add3_u32 v173, v159, v173, s91
	v_add3_u32 v153, v158, v153, s91
	v_add3_u32 v151, v156, v151, s91
	v_and_b32_e32 v172, 0xffff0000, v172
	v_and_b32_e32 v174, 0xffff0000, v173
	v_or_b32_sdwa v173, v172, v151 dst_sel:DWORD dst_unused:UNUSED_PAD src0_sel:DWORD src1_sel:WORD_1
	v_or_b32_sdwa v172, v174, v153 dst_sel:DWORD dst_unused:UNUSED_PAD src0_sel:DWORD src1_sel:WORD_1
	v_lshl_add_u64 v[174:175], v[146:147], 0, v[178:179]
	v_pk_mul_f32 v[140:141], v[140:141], v[176:177] op_sel_hi:[1,0]
	v_pk_mul_f32 v[138:139], v[138:139], v[176:177] op_sel_hi:[1,0]
	global_store_dwordx2 v[174:175], v[172:173], off
	v_and_b32_sdwa v172, v141, v205 dst_sel:DWORD dst_unused:UNUSED_PAD src0_sel:WORD_1 src1_sel:DWORD
	v_and_b32_sdwa v173, v139, v205 dst_sel:DWORD dst_unused:UNUSED_PAD src0_sel:WORD_1 src1_sel:DWORD
	v_and_b32_sdwa v151, v140, v205 dst_sel:DWORD dst_unused:UNUSED_PAD src0_sel:WORD_1 src1_sel:DWORD
	v_and_b32_sdwa v153, v138, v205 dst_sel:DWORD dst_unused:UNUSED_PAD src0_sel:WORD_1 src1_sel:DWORD
	v_add3_u32 v172, v141, v172, s91
	v_add3_u32 v173, v139, v173, s91
	v_add3_u32 v153, v138, v153, s91
	v_add3_u32 v151, v140, v151, s91
	v_and_b32_e32 v172, 0xffff0000, v172
	v_and_b32_e32 v177, 0xffff0000, v173
	v_or_b32_sdwa v173, v172, v151 dst_sel:DWORD dst_unused:UNUSED_PAD src0_sel:DWORD src1_sel:WORD_1
	v_or_b32_sdwa v172, v177, v153 dst_sel:DWORD dst_unused:UNUSED_PAD src0_sel:DWORD src1_sel:WORD_1
	v_pk_mul_f32 v[136:137], v[136:137], v[176:177] op_sel_hi:[1,0]
	v_pk_mul_f32 v[134:135], v[134:135], v[176:177] op_sel_hi:[1,0]
	global_store_dwordx2 v[174:175], v[172:173], off offset:512
	v_and_b32_sdwa v172, v137, v205 dst_sel:DWORD dst_unused:UNUSED_PAD src0_sel:WORD_1 src1_sel:DWORD
	v_and_b32_sdwa v173, v135, v205 dst_sel:DWORD dst_unused:UNUSED_PAD src0_sel:WORD_1 src1_sel:DWORD
	v_and_b32_sdwa v151, v136, v205 dst_sel:DWORD dst_unused:UNUSED_PAD src0_sel:WORD_1 src1_sel:DWORD
	v_and_b32_sdwa v153, v134, v205 dst_sel:DWORD dst_unused:UNUSED_PAD src0_sel:WORD_1 src1_sel:DWORD
	v_add3_u32 v172, v137, v172, s91
	v_add3_u32 v173, v135, v173, s91
	v_add3_u32 v153, v134, v153, s91
	v_add3_u32 v151, v136, v151, s91
	v_and_b32_e32 v172, 0xffff0000, v172
	v_and_b32_e32 v177, 0xffff0000, v173
	v_or_b32_sdwa v173, v172, v151 dst_sel:DWORD dst_unused:UNUSED_PAD src0_sel:DWORD src1_sel:WORD_1
	v_or_b32_sdwa v172, v177, v153 dst_sel:DWORD dst_unused:UNUSED_PAD src0_sel:DWORD src1_sel:WORD_1
	v_pk_mul_f32 v[132:133], v[132:133], v[176:177] op_sel_hi:[1,0]
	v_pk_mul_f32 v[130:131], v[130:131], v[176:177] op_sel_hi:[1,0]
	global_store_dwordx2 v[174:175], v[172:173], off offset:1024
	v_and_b32_sdwa v172, v133, v205 dst_sel:DWORD dst_unused:UNUSED_PAD src0_sel:WORD_1 src1_sel:DWORD
	v_and_b32_sdwa v173, v131, v205 dst_sel:DWORD dst_unused:UNUSED_PAD src0_sel:WORD_1 src1_sel:DWORD
	v_and_b32_sdwa v151, v132, v205 dst_sel:DWORD dst_unused:UNUSED_PAD src0_sel:WORD_1 src1_sel:DWORD
	v_and_b32_sdwa v153, v130, v205 dst_sel:DWORD dst_unused:UNUSED_PAD src0_sel:WORD_1 src1_sel:DWORD
	v_add3_u32 v172, v133, v172, s91
	v_add3_u32 v173, v131, v173, s91
	v_add3_u32 v153, v130, v153, s91
	v_add3_u32 v151, v132, v151, s91
	v_and_b32_e32 v172, 0xffff0000, v172
	v_and_b32_e32 v176, 0xffff0000, v173
	v_or_b32_sdwa v173, v172, v151 dst_sel:DWORD dst_unused:UNUSED_PAD src0_sel:DWORD src1_sel:WORD_1
	v_or_b32_sdwa v172, v176, v153 dst_sel:DWORD dst_unused:UNUSED_PAD src0_sel:DWORD src1_sel:WORD_1
	global_store_dwordx2 v[174:175], v[172:173], off offset:1536
	v_pk_mul_f32 v[180:181], v[2:3], v[158:159]
	v_pk_mul_f32 v[182:183], v[18:19], v[158:159]
	v_pk_mul_f32 v[184:185], v[34:35], v[158:159]
	v_pk_mul_f32 v[186:187], v[50:51], v[158:159]
	v_pk_fma_f32 v[180:181], v[4:5], v[156:157], v[180:181]
	v_pk_fma_f32 v[182:183], v[20:21], v[156:157], v[182:183]
	v_pk_fma_f32 v[184:185], v[36:37], v[156:157], v[184:185]
	v_pk_fma_f32 v[186:187], v[52:53], v[156:157], v[186:187]
	v_pk_fma_f32 v[180:181], v[6:7], v[138:139], v[180:181]
	v_pk_fma_f32 v[182:183], v[22:23], v[138:139], v[182:183]
	v_pk_fma_f32 v[184:185], v[38:39], v[138:139], v[184:185]
	v_pk_fma_f32 v[186:187], v[54:55], v[138:139], v[186:187]
	v_pk_fma_f32 v[180:181], v[8:9], v[140:141], v[180:181]
	v_pk_fma_f32 v[182:183], v[24:25], v[140:141], v[182:183]
	v_pk_fma_f32 v[184:185], v[40:41], v[140:141], v[184:185]
	v_pk_fma_f32 v[186:187], v[56:57], v[140:141], v[186:187]
	v_pk_fma_f32 v[180:181], v[10:11], v[134:135], v[180:181]
	v_pk_fma_f32 v[182:183], v[26:27], v[134:135], v[182:183]
	v_pk_fma_f32 v[184:185], v[42:43], v[134:135], v[184:185]
	v_pk_fma_f32 v[186:187], v[58:59], v[134:135], v[186:187]
	v_pk_fma_f32 v[180:181], v[12:13], v[136:137], v[180:181]
	v_pk_fma_f32 v[182:183], v[28:29], v[136:137], v[182:183]
	v_pk_fma_f32 v[184:185], v[44:45], v[136:137], v[184:185]
	v_pk_fma_f32 v[186:187], v[60:61], v[136:137], v[186:187]
	v_pk_fma_f32 v[180:181], v[14:15], v[130:131], v[180:181]
	v_pk_fma_f32 v[182:183], v[30:31], v[130:131], v[182:183]
	v_pk_fma_f32 v[184:185], v[46:47], v[130:131], v[184:185]
	v_pk_fma_f32 v[186:187], v[62:63], v[130:131], v[186:187]
	v_pk_fma_f32 v[180:181], v[16:17], v[132:133], v[180:181]
	v_pk_fma_f32 v[182:183], v[32:33], v[132:133], v[182:183]
	v_pk_fma_f32 v[184:185], v[48:49], v[132:133], v[184:185]
	v_pk_fma_f32 v[186:187], v[64:65], v[132:133], v[186:187]
	v_add_f32_e32 v151, v180, v181
	v_add_f32_e32 v153, v182, v183
	v_add_f32_e32 v172, v184, v185
	v_add_f32_e32 v173, v186, v187
	v_pk_mul_f32 v[180:181], v[66:67], v[158:159]
	v_pk_mul_f32 v[182:183], v[82:83], v[158:159]
	v_pk_mul_f32 v[184:185], v[98:99], v[158:159]
	v_pk_mul_f32 v[186:187], v[114:115], v[158:159]
	v_pk_fma_f32 v[180:181], v[68:69], v[156:157], v[180:181]
	v_pk_fma_f32 v[182:183], v[84:85], v[156:157], v[182:183]
	v_pk_fma_f32 v[184:185], v[100:101], v[156:157], v[184:185]
	v_pk_fma_f32 v[186:187], v[116:117], v[156:157], v[186:187]
	v_pk_fma_f32 v[180:181], v[70:71], v[138:139], v[180:181]
	v_pk_fma_f32 v[182:183], v[86:87], v[138:139], v[182:183]
	v_pk_fma_f32 v[184:185], v[102:103], v[138:139], v[184:185]
	v_pk_fma_f32 v[186:187], v[118:119], v[138:139], v[186:187]
	v_pk_fma_f32 v[180:181], v[72:73], v[140:141], v[180:181]
	v_pk_fma_f32 v[182:183], v[88:89], v[140:141], v[182:183]
	v_pk_fma_f32 v[184:185], v[104:105], v[140:141], v[184:185]
	v_pk_fma_f32 v[186:187], v[120:121], v[140:141], v[186:187]
	v_pk_fma_f32 v[180:181], v[74:75], v[134:135], v[180:181]
	v_pk_fma_f32 v[182:183], v[90:91], v[134:135], v[182:183]
	v_pk_fma_f32 v[184:185], v[106:107], v[134:135], v[184:185]
	v_pk_fma_f32 v[186:187], v[122:123], v[134:135], v[186:187]
	v_pk_fma_f32 v[180:181], v[76:77], v[136:137], v[180:181]
	v_pk_fma_f32 v[182:183], v[92:93], v[136:137], v[182:183]
	v_pk_fma_f32 v[184:185], v[108:109], v[136:137], v[184:185]
	v_pk_fma_f32 v[186:187], v[124:125], v[136:137], v[186:187]
	v_pk_fma_f32 v[180:181], v[78:79], v[130:131], v[180:181]
	v_pk_fma_f32 v[182:183], v[94:95], v[130:131], v[182:183]
	v_pk_fma_f32 v[184:185], v[110:111], v[130:131], v[184:185]
	v_pk_fma_f32 v[186:187], v[126:127], v[130:131], v[186:187]
	v_pk_fma_f32 v[180:181], v[80:81], v[132:133], v[180:181]
	v_pk_fma_f32 v[182:183], v[96:97], v[132:133], v[182:183]
	v_pk_fma_f32 v[184:185], v[112:113], v[132:133], v[184:185]
	v_pk_fma_f32 v[186:187], v[128:129], v[132:133], v[186:187]
	v_add_f32_e32 v174, v180, v181
	v_add_f32_e32 v175, v182, v183
	v_add_f32_e32 v176, v184, v185
	v_add_f32_e32 v130, v186, v187
	v_cndmask_b32_e32 v131, v151, v174, vcc
	v_cndmask_b32_e32 v132, v153, v175, vcc
	v_cndmask_b32_e32 v133, v172, v176, vcc
	v_cndmask_b32_e32 v134, v173, v130, vcc
	ds_bpermute_b32 v131, v166, v131
	ds_bpermute_b32 v132, v166, v132
	ds_bpermute_b32 v133, v166, v133
	ds_bpermute_b32 v134, v166, v134
	v_cndmask_b32_e32 v180, v174, v151, vcc
	v_cndmask_b32_e32 v181, v175, v153, vcc
	v_cndmask_b32_e32 v182, v176, v172, vcc
	v_cndmask_b32_e32 v183, v130, v173, vcc
	s_waitcnt lgkmcnt(0)
	v_add_f32_e32 v131, v180, v131
	v_add_f32_e32 v132, v181, v132
	v_add_f32_e32 v133, v182, v133
	v_add_f32_e32 v130, v183, v134
	v_cndmask_b32_e64 v134, v131, v133, s[38:39]
	v_cndmask_b32_e64 v131, v133, v131, s[38:39]
	ds_bpermute_b32 v133, v167, v134
	s_waitcnt lgkmcnt(0)
	v_add_f32_e32 v131, v131, v133
	v_cndmask_b32_e64 v133, v132, v130, s[38:39]
	v_cndmask_b32_e64 v130, v130, v132, s[38:39]
	ds_bpermute_b32 v132, v167, v133
	s_waitcnt lgkmcnt(0)
	v_add_f32_e32 v130, v130, v132
	v_cndmask_b32_e64 v132, v131, v130, s[40:41]
	v_cndmask_b32_e64 v130, v130, v131, s[40:41]
	ds_bpermute_b32 v131, v168, v132
	s_waitcnt lgkmcnt(0)
	v_add_f32_e32 v130, v130, v131
	ds_bpermute_b32 v131, v169, v130
	s_waitcnt lgkmcnt(0)
	v_add_f32_e32 v130, v130, v131
	ds_bpermute_b32 v131, v170, v130
	s_waitcnt lgkmcnt(0)
	v_add_f32_e32 v130, v130, v131
	ds_bpermute_b32 v131, v171, v130
	s_and_saveexec_b64 s[56:57], s[42:43]
	s_cbranch_execz .LBB0_641
	s_waitcnt lgkmcnt(0)
	v_add_f32_e32 v130, v130, v131
	v_mov_b32_e32 v131, v241
	v_add_f32_e32 v130, v130, v131
	v_cmp_ngt_f32_e64 s[46:47], 0, v130
	s_and_saveexec_b64 s[8:9], s[46:47]
	s_xor_b64 s[54:55], exec, s[8:9]
	s_cbranch_execz .LBB0_647
	v_mul_f32_e32 v131, 0xbfb8aa3b, v130
	v_rndne_f32_e32 v132, v131
	s_mov_b32 s8, 0xbfb8aa3b
	v_sub_f32_e32 v133, v131, v132
	v_fma_f32 v131, v130, s8, -v131
	v_fmac_f32_e32 v131, 0xb2a5705f, v130
	v_add_f32_e32 v131, v133, v131
	v_cvt_i32_f32_e32 v132, v132
	v_exp_f32_e32 v131, v131
	s_mov_b32 s8, 0x42ce8ed0
	v_cmp_nlt_f32_e64 s[46:47], s8, v130
	s_mov_b32 s8, 0xc2b17218
	v_ldexp_f32 v131, v131, v132
	v_cndmask_b32_e64 v131, 0, v131, s[46:47]
	v_cmp_ngt_f32_e64 s[46:47], s8, v130
	s_mov_b32 s8, 0x3f2aaaab
	s_nop 0
	v_cndmask_b32_e64 v151, v220, v131, s[46:47]
	v_add_f32_e32 v132, 1.0, v151
	v_add_f32_e32 v130, -1.0, v132
	v_sub_f32_e32 v131, v130, v132
	v_add_f32_e32 v131, 1.0, v131
	v_sub_f32_e32 v130, v151, v130
	v_add_f32_e32 v133, v130, v131
	v_frexp_mant_f32_e32 v134, v132
	v_cvt_f64_f32_e32 v[130:131], v132
	v_frexp_exp_i32_f64_e32 v130, v[130:131]
	v_cmp_gt_f32_e64 s[46:47], s8, v134
	s_mov_b32 s8, 0x3f317218
	s_nop 0
	v_subbrev_co_u32_e64 v138, s[46:47], 0, v130, s[46:47]
	v_sub_u32_e32 v130, 0, v138
	v_ldexp_f32 v131, v132, v130
	v_add_f32_e32 v132, -1.0, v131
	v_add_f32_e32 v134, 1.0, v131
	v_ldexp_f32 v130, v133, v130
	v_add_f32_e32 v133, 1.0, v132
	v_add_f32_e32 v135, -1.0, v134
	v_sub_f32_e32 v133, v131, v133
	v_sub_f32_e32 v131, v131, v135
	v_add_f32_e32 v133, v130, v133
	v_add_f32_e32 v130, v130, v131
	v_add_f32_e32 v139, v134, v130
	v_rcp_f32_e32 v141, v139
	v_sub_f32_e32 v131, v134, v139
	v_add_f32_e32 v140, v130, v131
	v_add_f32_e32 v131, v132, v133
	v_mul_f32_e32 v156, v131, v141
	v_sub_f32_e32 v130, v132, v131
	v_mul_f32_e32 v132, v139, v156
	v_fma_f32 v134, v156, v139, -v132
	v_fmac_f32_e32 v134, v156, v140
	v_add_f32_e32 v153, v133, v130
	v_add_f32_e32 v130, v132, v134
	v_sub_f32_e32 v133, v131, v130
	v_pk_add_f32 v[136:137], v[130:131], v[132:133] neg_lo:[0,1] neg_hi:[0,1]
	v_mov_b32_e32 v135, v130
	v_pk_add_f32 v[130:131], v[136:137], v[134:135] neg_lo:[0,1] neg_hi:[0,1]
	s_nop 0
	v_add_f32_e32 v131, v153, v131
	v_add_f32_e32 v130, v130, v131
	v_add_f32_e32 v131, v133, v130
	v_mul_f32_e32 v153, v141, v131
	v_mul_f32_e32 v132, v139, v153
	v_fma_f32 v134, v153, v139, -v132
	v_fmac_f32_e32 v134, v153, v140
	v_sub_f32_e32 v133, v133, v131
	v_add_f32_e32 v139, v130, v133
	v_add_f32_e32 v130, v132, v134
	v_sub_f32_e32 v133, v131, v130
	v_pk_add_f32 v[136:137], v[130:131], v[132:133] neg_lo:[0,1] neg_hi:[0,1]
	v_mov_b32_e32 v135, v130
	v_pk_add_f32 v[130:131], v[136:137], v[134:135] neg_lo:[0,1] neg_hi:[0,1]
	s_nop 0
	v_add_f32_e32 v131, v139, v131
	v_add_f32_e32 v130, v130, v131
	v_add_f32_e32 v131, v156, v153
	v_add_f32_e32 v130, v133, v130
	v_sub_f32_e32 v132, v131, v156
	v_mul_f32_e32 v130, v141, v130
	v_sub_f32_e32 v132, v153, v132
	v_add_f32_e32 v132, v132, v130
	v_add_f32_e32 v134, v131, v132
	v_mul_f32_e32 v135, v134, v134
	v_fmamk_f32 v130, v135, 0x3e9b6dac, v207
	v_fmaak_f32 v197, v135, v130, 0x3f2aaada
	v_cvt_f32_i32_e32 v130, v138
	v_sub_f32_e32 v131, v134, v131
	v_sub_f32_e32 v131, v132, v131
	v_ldexp_f32 v136, v131, 1
	v_mul_f32_e32 v131, v134, v135
	v_ldexp_f32 v133, v134, 1
	v_pk_mul_f32 v[134:135], v[130:131], v[196:197]
	s_nop 0
	v_fma_f32 v132, v130, s8, -v134
	v_fmac_f32_e32 v132, 0xb102e308, v130
	v_pk_add_f32 v[130:131], v[134:135], v[132:133]
	s_mov_b32 s8, 0x7f800000
	v_sub_f32_e32 v133, v131, v133
	v_sub_f32_e32 v133, v135, v133
	v_add_f32_e32 v137, v136, v133
	v_mov_b32_e32 v136, v134
	v_pk_add_f32 v[134:135], v[130:131], v[134:135] neg_lo:[0,1] neg_hi:[0,1]
	v_pk_add_f32 v[138:139], v[130:131], v[136:137]
	v_mov_b32_e32 v133, v130
	v_mov_b32_e32 v135, v139
	v_pk_add_f32 v[140:141], v[132:133], v[134:135] neg_lo:[0,1] neg_hi:[0,1]
	v_pk_add_f32 v[132:133], v[132:133], v[134:135]
	v_mov_b32_e32 v136, v137
	v_pk_add_f32 v[134:135], v[132:133], v[130:131] op_sel:[1,0] op_sel_hi:[0,1] neg_lo:[0,1] neg_hi:[0,1]
	v_pk_add_f32 v[156:157], v[138:139], v[134:135] op_sel_hi:[1,0] neg_lo:[0,1] neg_hi:[0,1]
	v_mov_b32_e32 v138, v139
	v_mov_b32_e32 v139, v133
	v_pk_mov_b32 v[134:135], v[130:131], v[134:135] op_sel:[1,0]
	v_mov_b32_e32 v137, v130
	v_pk_add_f32 v[134:135], v[138:139], v[134:135] neg_lo:[0,1] neg_hi:[0,1]
	v_mov_b32_e32 v156, v140
	v_pk_add_f32 v[130:131], v[136:137], v[134:135] neg_lo:[0,1] neg_hi:[0,1]
	v_mov_b32_e32 v141, v133
	v_pk_add_f32 v[134:135], v[156:157], v[130:131]
	v_cmp_neq_f32_e64 s[46:47], s8, v151
	v_pk_add_f32 v[136:137], v[134:135], v[134:135] op_sel:[0,1] op_sel_hi:[1,0]
	s_mov_b32 s8, 0x33800000
	v_pk_add_f32 v[132:133], v[132:133], v[136:137] op_sel:[1,0] op_sel_hi:[0,1]
	v_mov_b32_e32 v135, v132
	v_pk_add_f32 v[138:139], v[134:135], v[140:141] neg_lo:[0,1] neg_hi:[0,1]
	v_mov_b32_e32 v131, v136
	v_sub_f32_e32 v133, v134, v138
	v_pk_add_f32 v[130:131], v[130:131], v[138:139] neg_lo:[0,1] neg_hi:[0,1]
	v_sub_f32_e32 v133, v140, v133
	v_add_f32_e32 v130, v130, v133
	v_add_f32_e32 v130, v130, v131
	v_add_f32_e32 v130, v132, v130
	v_cndmask_b32_e64 v130, v220, v130, s[46:47]
	v_cmp_lt_f32_e64 s[46:47], |v151|, s8
	s_nop 1
	v_cndmask_b32_e64 v130, v130, v151, s[46:47]
	v_xor_b32_e32 v131, 0x80000000, v130
